# speedup vs baseline: 1.0042x; 1.0042x over previous
; #define MFMA16(a, b, c) __builtin_amdgcn_mfma_f32_16x16x32_bf16((a), (b), (c), 0, 0, 0)
; __device__ __forceinline__ void hgrn_block(const Params& p, int bh, char* smem) {
;     ...
;     {
;       float dc[4];
; #pragma unroll
;       for (int j = 0; j < 4; ++j) dc[j] = dec[wid * 16 + fq * 4 + j];
; #pragma unroll
;       for (int vt = 0; vt < 8; ++vt) {
;         st[vt][0] *= dc[0]; st[vt][1] *= dc[1]; st[vt][2] *= dc[2]; st[vt][3] *= dc[3];
;       }
; #pragma unroll
;       for (int kk = 0; kk < 2; ++kk) {
;         bf16x8 kf = *(const bf16x8*)(KSTT + (wid * 16 + fr) * 72 + kk * 32 + fq * 8);
; #pragma unroll
;         for (int vt = 0; vt < 8; ++vt) {
;           bf16x8 vf = *(const bf16x8*)(VT + (vt * 16 + fr) * 72 + kk * 32 + fq * 8);
;           st[vt] = MFMA16(kf, vf, st[vt]);
;         }
;       }
;     }
.LBB0_598:
	s_or_b64 exec, exec, s[52:53]
	ds_read_b128 v[74:77], v130
	ds_read_b128 v[78:81], v54 offset:52224
	ds_read_b128 v[212:215], v131
	ds_read_b128 v[216:219], v131 offset:2304
	ds_read_b128 v[220:223], v131 offset:4608
	ds_read_b128 v[224:227], v131 offset:6912
	ds_read_b128 v[228:231], v131 offset:9216
	ds_read_b128 v[232:235], v131 offset:11520
	ds_read_b128 v[236:239], v131 offset:13824
	ds_read_b128 v[240:243], v131 offset:16128
	ds_read_b128 v[174:177], v54 offset:52288
	s_add_i32 s77, s77, -1
	v_lshl_add_u64 v[60:61], v[60:61], 0, s[48:49]
	v_lshl_add_u64 v[64:65], v[64:65], 0, s[48:49]
	s_cmp_lg_u32 s77, 0
	s_waitcnt lgkmcnt(10)
	v_pk_mul_f32 v[0:1], v[0:1], v[74:75]
	v_pk_mul_f32 v[2:3], v[2:3], v[76:77]
	v_pk_mul_f32 v[4:5], v[4:5], v[74:75]
	v_pk_mul_f32 v[6:7], v[6:7], v[76:77]
	v_pk_mul_f32 v[8:9], v[8:9], v[74:75]
	v_pk_mul_f32 v[10:11], v[10:11], v[76:77]
	v_pk_mul_f32 v[12:13], v[12:13], v[74:75]
	v_pk_mul_f32 v[14:15], v[14:15], v[76:77]
	v_pk_mul_f32 v[16:17], v[16:17], v[74:75]
	v_pk_mul_f32 v[18:19], v[18:19], v[76:77]
	v_pk_mul_f32 v[20:21], v[20:21], v[74:75]
	v_pk_mul_f32 v[22:23], v[22:23], v[76:77]
	v_pk_mul_f32 v[24:25], v[24:25], v[74:75]
	v_pk_mul_f32 v[26:27], v[26:27], v[76:77]
	v_pk_mul_f32 v[28:29], v[28:29], v[74:75]
	v_pk_mul_f32 v[30:31], v[30:31], v[76:77]
	s_waitcnt lgkmcnt(8)
	v_mfma_f32_16x16x32_bf16 v[0:3], v[78:81], v[212:215], v[0:3]
	ds_read_b128 v[212:215], v131 offset:64
	s_waitcnt vmcnt(25)
	v_mov_b32_e32 v157, v136
	s_waitcnt vmcnt(22)
	v_mov_b32_e32 v159, v139
	s_waitcnt lgkmcnt(8)
	v_mfma_f32_16x16x32_bf16 v[4:7], v[78:81], v[216:219], v[4:7]
	ds_read_b128 v[216:219], v131 offset:2368
	s_waitcnt vmcnt(19)
	v_mov_b32_e32 v158, v141
	s_waitcnt vmcnt(16)
	v_mov_b32_e32 v156, v143
	s_waitcnt lgkmcnt(8)
	v_mfma_f32_16x16x32_bf16 v[8:11], v[78:81], v[220:223], v[8:11]
	ds_read_b128 v[220:223], v131 offset:4672
	s_waitcnt vmcnt(13)
	v_mov_b32_e32 v155, v145
	s_waitcnt vmcnt(10)
	v_mov_b32_e32 v154, v147
	s_waitcnt lgkmcnt(8)
	v_mfma_f32_16x16x32_bf16 v[12:15], v[78:81], v[224:227], v[12:15]
	ds_read_b128 v[224:227], v131 offset:6976
	s_waitcnt vmcnt(7)
	v_mov_b32_e32 v153, v149
	s_waitcnt vmcnt(4)
	v_mov_b32_e32 v152, v151
	s_waitcnt lgkmcnt(8)
	v_mfma_f32_16x16x32_bf16 v[16:19], v[78:81], v[228:231], v[16:19]
	ds_read_b128 v[228:231], v131 offset:9280
	v_mov_b32_e32 v165, v134
	v_mov_b32_e32 v162, v137
	s_waitcnt lgkmcnt(8)
	v_mfma_f32_16x16x32_bf16 v[20:23], v[78:81], v[232:235], v[20:23]
	ds_read_b128 v[232:235], v131 offset:11584
	v_mov_b32_e32 v161, v140
	v_mov_b32_e32 v160, v142
	s_waitcnt lgkmcnt(8)
	v_mfma_f32_16x16x32_bf16 v[24:27], v[78:81], v[236:239], v[24:27]
	ds_read_b128 v[236:239], v131 offset:13888
	v_mov_b32_e32 v164, v144
	v_mov_b32_e32 v163, v146
	s_waitcnt lgkmcnt(8)
	v_mfma_f32_16x16x32_bf16 v[28:31], v[78:81], v[240:243], v[28:31]
	ds_read_b128 v[240:243], v131 offset:16192
	v_mov_b32_e32 v166, v148
	v_mov_b32_e32 v167, v150
	s_waitcnt lgkmcnt(7)
	v_mfma_f32_16x16x32_bf16 v[0:3], v[174:177], v[212:215], v[0:3]
	s_waitcnt lgkmcnt(6)
	v_mfma_f32_16x16x32_bf16 v[4:7], v[174:177], v[216:219], v[4:7]
	s_waitcnt lgkmcnt(5)
	v_mfma_f32_16x16x32_bf16 v[8:11], v[174:177], v[220:223], v[8:11]
	s_waitcnt lgkmcnt(4)
	v_mfma_f32_16x16x32_bf16 v[12:15], v[174:177], v[224:227], v[12:15]
	s_waitcnt lgkmcnt(3)
	v_mfma_f32_16x16x32_bf16 v[16:19], v[174:177], v[228:231], v[16:19]
	s_waitcnt lgkmcnt(2)
	v_mfma_f32_16x16x32_bf16 v[20:23], v[174:177], v[232:235], v[20:23]
	v_cvt_pk_bf16_f32 v48, v0, v1
	v_cvt_pk_bf16_f32 v49, v2, v3
	s_waitcnt lgkmcnt(1)
	v_mfma_f32_16x16x32_bf16 v[24:27], v[174:177], v[236:239], v[24:27]
	s_waitcnt lgkmcnt(0)
	s_barrier
; __device__ __forceinline__ float lo2f(unsigned u) { return __uint_as_float(u << 16); }
; __device__ __forceinline__ float hi2f(unsigned u) { return __uint_as_float(u & 0xffff0000u); }
; __device__ __forceinline__ float siluf_(float x) { return x * sigmoidf_(x); }
; __device__ __forceinline__ void hgrn_block(const Params& p, int bh, char* smem) {
;     ...
;     __syncthreads();
;     {
; #pragma unroll
;       for (int vt = 0; vt < 8; ++vt) {
;         uint2 o;
;         o.x = pack2(st[vt][0], st[vt][1]);
;         o.y = pack2(st[vt][2], st[vt][3]);
;         *(uint2*)(STT + (vt * 16 + fr) * 136 + wid * 16 + fq * 4) = o;
;       }
;     }
;     {
;       const int t = tt * 16 + fr;
;       float tot = ssq[t] + ssq[64 + t];
;       float rr = rsqrtf(tot * (1.f / 128.f) + EPS);
;       u16* op = p.MB + (tokb + t) * DM + h * 128;
; #pragma unroll
;       for (int i = 0; i < 4; ++i) {
;         const int v = (vh * 4 + i) * 16 + fq * 4;
;         float4 og = *(const float4*)(p.out_gain + v);
;         uint2 gg = rg[i];
;         uint2 w;
;         w.x = pack2(oc[i][0] * rr * og.x * siluf_(lo2f(gg.x)), oc[i][1] * rr * og.y * siluf_(hi2f(gg.x)));
;         w.y = pack2(oc[i][2] * rr * og.z * siluf_(lo2f(gg.y)), oc[i][3] * rr * og.w * siluf_(hi2f(gg.y)));
;         *(uint2*)(op + v) = w;
;       }
;     }
	v_mfma_f32_16x16x32_bf16 v[28:31], v[174:177], v[240:243], v[28:31]
	s_nop 1
	v_mov_b64_e32 v[76:77], v[196:197]
	v_mov_b64_e32 v[78:79], v[198:199]
	ds_write_b64 v132, v[48:49]
	v_cvt_pk_bf16_f32 v48, v4, v5
	v_cvt_pk_bf16_f32 v49, v6, v7
	ds_write_b64 v132, v[48:49] offset:4352
	v_cvt_pk_bf16_f32 v48, v8, v9
	v_cvt_pk_bf16_f32 v49, v10, v11
	ds_write_b64 v132, v[48:49] offset:8704
	v_cvt_pk_bf16_f32 v48, v12, v13
	v_cvt_pk_bf16_f32 v49, v14, v15
	ds_write_b64 v132, v[48:49] offset:13056
	v_cvt_pk_bf16_f32 v48, v16, v17
	v_cvt_pk_bf16_f32 v49, v18, v19
	ds_write_b64 v132, v[48:49] offset:17408
	v_cvt_pk_bf16_f32 v48, v20, v21
	v_cvt_pk_bf16_f32 v49, v22, v23
	ds_write_b64 v132, v[48:49] offset:21760
	v_cvt_pk_bf16_f32 v48, v24, v25
	v_cvt_pk_bf16_f32 v49, v26, v27
	ds_write_b64 v132, v[48:49] offset:26112
	v_cvt_pk_bf16_f32 v48, v28, v29
	v_cvt_pk_bf16_f32 v49, v30, v31
	ds_write_b64 v132, v[48:49] offset:30464
	ds_read2st64_b32 v[48:49], v55 offset1:1
	s_waitcnt vmcnt(3)
	v_lshlrev_b32_e32 v74, 16, v72
	v_and_b32_e32 v75, 0xffff0000, v72
	s_waitcnt lgkmcnt(0)
	v_add_f32_e32 v48, v48, v49
	v_fmamk_f32 v48, v48, 0x3c000000, v109
	v_cmp_gt_f32_e32 vcc, s75, v48
	v_mul_f32_e32 v49, 0x4b800000, v48
	s_nop 0
	v_cndmask_b32_e32 v48, v48, v49, vcc
	v_rsq_f32_e32 v48, v48
	s_nop 0
	v_mul_f32_e32 v49, 0x45800000, v48
	v_cndmask_b32_e32 v48, v48, v49, vcc
	v_mul_f32_e32 v49, 0xbfb8aa3b, v74
	v_exp_f32_e32 v49, v49
	s_nop 0
	v_add_f32_e32 v49, 1.0, v49
	v_rcp_f32_e32 v80, v49
	v_pk_mul_f32 v[44:45], v[44:45], v[48:49] op_sel_hi:[1,0]
	v_mul_f32_e32 v49, 0xbfb8aa3b, v75
	v_exp_f32_e32 v49, v49
	s_waitcnt vmcnt(0)
	v_pk_mul_f32 v[44:45], v[76:77], v[44:45]
	v_add_f32_e32 v49, 1.0, v49
	v_rcp_f32_e32 v81, v49
	s_nop 0
	v_pk_mul_f32 v[74:75], v[80:81], v[74:75]
	s_nop 0
	v_pk_mul_f32 v[44:45], v[74:75], v[44:45]
	s_nop 0
	v_cvt_pk_bf16_f32 v72, v44, v45
	v_lshlrev_b32_e32 v44, 16, v73
	v_mul_f32_e32 v49, 0xbfb8aa3b, v44
	v_exp_f32_e32 v49, v49
	v_and_b32_e32 v45, 0xffff0000, v73
	v_add_f32_e32 v49, 1.0, v49
	v_rcp_f32_e32 v74, v49
	v_pk_mul_f32 v[46:47], v[46:47], v[48:49] op_sel_hi:[1,0]
	v_mul_f32_e32 v49, 0xbfb8aa3b, v45
	v_exp_f32_e32 v49, v49
	v_pk_mul_f32 v[46:47], v[78:79], v[46:47]
	v_add_f32_e32 v49, 1.0, v49
	v_rcp_f32_e32 v75, v49
	s_nop 0
	v_pk_mul_f32 v[44:45], v[74:75], v[44:45]
	s_nop 0
	v_pk_mul_f32 v[44:45], v[44:45], v[46:47]
	v_lshlrev_b32_e32 v46, 16, v70
	v_cvt_pk_bf16_f32 v73, v44, v45
	v_lshl_add_u64 v[44:45], v[62:63], 0, s[46:47]
	global_store_dwordx2 v[44:45], v[72:73], off
	s_nop 1
	v_mov_b64_e32 v[72:73], v[200:201]
	v_mov_b64_e32 v[74:75], v[202:203]
	v_mul_f32_e32 v49, 0xbfb8aa3b, v46
	v_exp_f32_e32 v49, v49
	v_and_b32_e32 v47, 0xffff0000, v70
	v_lshl_add_u64 v[62:63], v[62:63], 0, s[50:51]
	v_add_f32_e32 v49, 1.0, v49
	v_rcp_f32_e32 v76, v49
	v_pk_mul_f32 v[40:41], v[40:41], v[48:49] op_sel_hi:[1,0]
	v_mul_f32_e32 v49, 0xbfb8aa3b, v47
	v_exp_f32_e32 v49, v49
	v_pk_mul_f32 v[40:41], v[72:73], v[40:41]
	v_add_f32_e32 v49, 1.0, v49
	v_rcp_f32_e32 v77, v49
	v_pk_mul_f32 v[42:43], v[42:43], v[48:49] op_sel_hi:[1,0]
	v_pk_mul_f32 v[46:47], v[76:77], v[46:47]
	s_nop 0
	v_pk_mul_f32 v[40:41], v[46:47], v[40:41]
	v_lshlrev_b32_e32 v46, 16, v71
	v_cvt_pk_bf16_f32 v40, v40, v41
	v_mul_f32_e32 v41, 0xbfb8aa3b, v46
	v_exp_f32_e32 v41, v41
	v_and_b32_e32 v47, 0xffff0000, v71
	v_pk_mul_f32 v[42:43], v[42:43], v[74:75]
	v_add_f32_e32 v41, 1.0, v41
	v_rcp_f32_e32 v70, v41
	v_mul_f32_e32 v41, 0xbfb8aa3b, v47
	v_exp_f32_e32 v41, v41
	s_nop 0
	v_add_f32_e32 v41, 1.0, v41
	v_rcp_f32_e32 v71, v41
	s_nop 0
	v_pk_mul_f32 v[46:47], v[70:71], v[46:47]
	s_nop 0
	v_pk_mul_f32 v[42:43], v[46:47], v[42:43]
	v_lshlrev_b32_e32 v46, 16, v68
	v_cvt_pk_bf16_f32 v41, v42, v43
	global_store_dwordx2 v[44:45], v[40:41], off offset:32
	s_nop 1
	v_mov_b64_e32 v[40:41], v[204:205]
	v_mov_b64_e32 v[42:43], v[206:207]
	v_mul_f32_e32 v49, 0xbfb8aa3b, v46
	v_exp_f32_e32 v49, v49
	v_and_b32_e32 v47, 0xffff0000, v68
	v_add_f32_e32 v49, 1.0, v49
	v_pk_mul_f32 v[36:37], v[36:37], v[48:49] op_sel_hi:[1,0]
	v_rcp_f32_e32 v70, v49
	v_pk_mul_f32 v[38:39], v[38:39], v[48:49] op_sel_hi:[1,0]
	v_pk_mul_f32 v[32:33], v[32:33], v[48:49] op_sel_hi:[1,0]
	v_pk_mul_f32 v[34:35], v[34:35], v[48:49] op_sel_hi:[1,0]
	v_pk_mul_f32 v[36:37], v[36:37], v[40:41]
	v_mul_f32_e32 v40, 0xbfb8aa3b, v47
	v_exp_f32_e32 v40, v40
	v_pk_mul_f32 v[38:39], v[38:39], v[42:43]
	v_add_f32_e32 v40, 1.0, v40
	v_rcp_f32_e32 v71, v40
	s_nop 0
	v_pk_mul_f32 v[40:41], v[70:71], v[46:47]
	s_nop 0
	v_pk_mul_f32 v[36:37], v[40:41], v[36:37]
	v_lshlrev_b32_e32 v40, 16, v69
	v_cvt_pk_bf16_f32 v36, v36, v37
	v_mul_f32_e32 v37, 0xbfb8aa3b, v40
	v_exp_f32_e32 v37, v37
	v_and_b32_e32 v41, 0xffff0000, v69
	v_add_f32_e32 v37, 1.0, v37
	v_rcp_f32_e32 v46, v37
	v_mul_f32_e32 v37, 0xbfb8aa3b, v41
	v_exp_f32_e32 v37, v37
	s_nop 0
	v_add_f32_e32 v37, 1.0, v37
	v_rcp_f32_e32 v47, v37
	s_nop 0
	v_pk_mul_f32 v[40:41], v[46:47], v[40:41]
	s_nop 0
	v_pk_mul_f32 v[38:39], v[40:41], v[38:39]
	v_lshlrev_b32_e32 v40, 16, v66
	v_cvt_pk_bf16_f32 v37, v38, v39
	global_store_dwordx2 v[44:45], v[36:37], off offset:64
	s_nop 1
	v_mov_b64_e32 v[36:37], v[208:209]
	v_mov_b64_e32 v[38:39], v[210:211]
	v_and_b32_e32 v41, 0xffff0000, v66
	v_mul_f32_e32 v42, 0xbfb8aa3b, v40
	v_exp_f32_e32 v42, v42
	v_pk_mul_f32 v[32:33], v[32:33], v[36:37]
	v_mul_f32_e32 v36, 0xbfb8aa3b, v41
	v_exp_f32_e32 v36, v36
	v_add_f32_e32 v42, 1.0, v42
	v_rcp_f32_e32 v42, v42
	v_pk_mul_f32 v[34:35], v[34:35], v[38:39]
	v_add_f32_e32 v36, 1.0, v36
	v_rcp_f32_e32 v43, v36
	s_nop 0
	v_pk_mul_f32 v[36:37], v[42:43], v[40:41]
	s_nop 0
	v_pk_mul_f32 v[32:33], v[36:37], v[32:33]
	v_lshlrev_b32_e32 v36, 16, v67
	v_cvt_pk_bf16_f32 v32, v32, v33
	v_mul_f32_e32 v33, 0xbfb8aa3b, v36
	v_exp_f32_e32 v33, v33
	v_and_b32_e32 v37, 0xffff0000, v67
	v_add_f32_e32 v33, 1.0, v33
	v_rcp_f32_e32 v40, v33
	v_mul_f32_e32 v33, 0xbfb8aa3b, v37
	v_exp_f32_e32 v33, v33
	s_nop 0
	v_add_f32_e32 v33, 1.0, v33
	v_rcp_f32_e32 v41, v33
	s_nop 0
	v_pk_mul_f32 v[36:37], v[40:41], v[36:37]
	s_nop 0
	v_pk_mul_f32 v[34:35], v[36:37], v[34:35]
	s_nop 0
	v_cvt_pk_bf16_f32 v33, v34, v35
	global_store_dwordx2 v[44:45], v[32:33], off offset:96
	s_cbranch_scc0 .LBB0_593

; __device__ __forceinline__ float exp2_(float x) { return __builtin_amdgcn_exp2f(x); }
; __device__ __forceinline__ float rcp_(float x) { return __builtin_amdgcn_rcpf(x); }
; __device__ __forceinline__ float lo2f(unsigned u) { return __uint_as_float(u << 16); }
; __device__ __forceinline__ float hi2f(unsigned u) { return __uint_as_float(u & 0xffff0000u); }
; __device__ __forceinline__ void hgrn_block(const Params& p, int bh, char* smem) {
;     ...
;       float off[2] = {0.f, 0.f}, gmid[2] = {0.f, 0.f}, gend[2] = {0.f, 0.f};
; #pragma unroll
;       for (int w = 0; w < 8; ++w)
; #pragma unroll
;         for (int e = 0; e < 2; ++e) {
;           float g = gsum[w * 128 + d0 + e];
;           if (w < wid) off[e] += g;
;           if (w < 4) gmid[e] += g;
;           gend[e] += g;
;         }
;       if (wid == 0) { dec[d0] = exp2_(gend[0]); dec[d0 + 1] = exp2_(gend[1]); }
;       const float egm[2] = {exp2_(gmid[0]), exp2_(gmid[1])};
;       const float eem[2] = {exp2_(gend[0] - gmid[0]), exp2_(gend[1] - gmid[1])};
;       float ks[2][8], vs[2][8];
; #pragma unroll
;       for (int r = 0; r < 8; ++r) {
;         const int t = wid * 8 + r;
;         float e0 = exp2_(gc[r][0] + off[0] - gmid[0]), e1 = exp2_(gc[r][1] + off[1] - gmid[1]);
;         float r0 = rcp_(e0), r1 = rcp_(e1);
;         float qa0 = qv[r][0] * e0, qa1 = qv[r][1] * e1;
;         float kb0 = kv[r][0] * r0, kb1 = kv[r][1] * r1;
;         *(unsigned*)(QA + t * 136 + d0) = pack2(qa0, qa1);
;         *(unsigned*)(KB + t * 136 + d0) = pack2(kb0, kb1);
;         *(unsigned*)(QIN + t * 136 + d0) = pack2(qa0 * egm[0], qa1 * egm[1]);
;         ks[0][r] = kb0 * eem[0];
;         ks[1][r] = kb1 * eem[1];
;         vs[0][r] = lo2f(vv[r]);
;         vs[1][r] = hi2f(vv[r]);
;       }
; #pragma unroll
;       for (int e = 0; e < 2; ++e) {
;         *(uint4*)(KSTT + (d0 + e) * 72 + wid * 8) = pack8(ks[e]);
;         *(uint4*)(VT + (d0 + e) * 72 + wid * 8) = pack8(vs[e]);
;       }
.LBB0_603:
	s_or_b64 exec, exec, s[52:53]
	v_cndmask_b32_e64 v169, 0, v169, s[8:9]
	v_cndmask_b32_e64 v170, 0, v170, s[8:9]
	v_add_f32_e32 v40, v40, v169
	v_cndmask_b32_e64 v40, v169, v40, s[10:11]
	v_add_f32_e32 v41, v41, v170
	v_cndmask_b32_e64 v41, v170, v41, s[10:11]
	v_add_f32_e32 v34, v34, v40
	v_cndmask_b32_e64 v34, v40, v34, s[12:13]
	v_add_f32_e32 v35, v35, v41
	v_cndmask_b32_e64 v35, v41, v35, s[12:13]
	v_add_f32_e32 v36, v36, v34
	v_cndmask_b32_e64 v34, v34, v36, s[14:15]
	v_add_f32_e32 v36, v37, v35
	v_cndmask_b32_e64 v35, v35, v36, s[14:15]
	v_add_f32_e32 v36, v42, v34
	v_cndmask_b32_e64 v34, v34, v36, s[16:17]
	v_add_f32_e32 v36, v43, v35
	v_cndmask_b32_e64 v35, v35, v36, s[16:17]
	v_add_f32_e32 v36, v44, v34
	v_cndmask_b32_e64 v34, v34, v36, s[18:19]
	v_add_f32_e32 v36, v45, v35
	v_cndmask_b32_e64 v35, v35, v36, s[18:19]
	v_add_f32_e32 v36, v46, v34
	v_cndmask_b32_e64 v34, v34, v36, s[20:21]
	v_add_f32_e32 v36, v47, v35
	v_cndmask_b32_e64 v35, v35, v36, s[20:21]
	v_add_f32_e32 v36, v48, v34
	v_cndmask_b32_e64 v169, v34, v36, s[22:23]
	v_add_f32_e32 v34, v49, v35
	v_cndmask_b32_e64 v170, v35, v34, s[22:23]
	v_add_f32_e32 v104, v104, v169
	v_add_f32_e32 v105, v105, v170
	v_sub_f32_e32 v104, v104, v38
	v_sub_f32_e32 v105, v105, v33
	v_exp_f32_e32 v104, v104
	v_exp_f32_e32 v105, v105
	v_add_f32_e32 v102, v102, v169
	v_add_f32_e32 v103, v103, v170
	v_lshlrev_b32_e32 v36, 16, v162
	v_and_b32_e32 v37, 0xffff0000, v162
	v_lshlrev_b32_e32 v46, 16, v163
	v_and_b32_e32 v47, 0xffff0000, v163
	v_exp_f32_e32 v162, v38
	v_exp_f32_e32 v163, v33
	v_sub_f32_e32 v102, v102, v38
	v_sub_f32_e32 v103, v103, v33
	v_exp_f32_e32 v102, v102
	v_exp_f32_e32 v103, v103
	v_lshlrev_b32_e32 v34, 16, v165
	v_and_b32_e32 v35, 0xffff0000, v165
	v_sub_f32_e32 v39, v39, v33
	v_pk_mul_f32 v[34:35], v[104:105], v[34:35]
	v_lshlrev_b32_e32 v44, 16, v164
	v_and_b32_e32 v45, 0xffff0000, v164
	v_sub_f32_e32 v164, v168, v38
	v_exp_f32_e32 v168, v39
	v_cvt_pk_bf16_f32 v39, v34, v35
	v_pk_mul_f32 v[34:35], v[162:163], v[34:35]
	v_lshlrev_b32_e32 v40, 16, v161
	v_and_b32_e32 v41, 0xffff0000, v161
	v_lshlrev_b32_e32 v42, 16, v160
	v_and_b32_e32 v43, 0xffff0000, v160
	v_lshlrev_b32_e32 v160, 16, v167
	v_and_b32_e32 v161, 0xffff0000, v167
	v_rcp_f32_e32 v167, v105
	v_cvt_pk_bf16_f32 v105, v34, v35
	v_rcp_f32_e32 v34, v102
	v_rcp_f32_e32 v35, v103
	v_pk_mul_f32 v[36:37], v[102:103], v[36:37]
	v_lshlrev_b32_e32 v48, 16, v166
	v_and_b32_e32 v49, 0xffff0000, v166
	v_pk_mul_f32 v[34:35], v[86:87], v[34:35]
	v_cvt_pk_bf16_f32 v86, v36, v37
	v_pk_mul_f32 v[36:37], v[162:163], v[36:37]
	ds_write2_b32 v121, v39, v86 offset1:68
	v_cvt_pk_bf16_f32 v39, v34, v35
	v_cvt_pk_bf16_f32 v36, v36, v37
	v_mov_b32_e32 v37, v34
	v_add_f32_e32 v34, v100, v169
	v_rcp_f32_e32 v166, v104
	v_sub_f32_e32 v34, v34, v38
	v_exp_f32_e32 v86, v34
	v_add_f32_e32 v34, v101, v170
	v_sub_f32_e32 v34, v34, v33
	v_exp_f32_e32 v87, v34
	v_pk_mul_f32 v[90:91], v[90:91], v[166:167]
	v_add_u32_e32 v102, 0x4400, v121
	v_cvt_pk_bf16_f32 v104, v90, v91
	ds_write2_b32 v102, v104, v39 offset1:68
	v_add_u32_e32 v39, 0x8800, v121
	v_mov_b32_e32 v34, v91
	ds_write2_b32 v39, v105, v36 offset1:68
	v_mov_b32_e32 v36, v90
	v_pk_mul_f32 v[90:91], v[168:169], v[34:35] op_sel_hi:[0,1]
	v_rcp_f32_e32 v34, v86
	v_rcp_f32_e32 v35, v87
	v_pk_mul_f32 v[40:41], v[86:87], v[40:41]
	v_exp_f32_e32 v164, v164
	v_cvt_pk_bf16_f32 v86, v40, v41
	v_pk_mul_f32 v[34:35], v[84:85], v[34:35]
	v_add_f32_e32 v84, v98, v169
	v_add_f32_e32 v85, v99, v170
	v_sub_f32_e32 v84, v84, v38
	v_sub_f32_e32 v85, v85, v33
	v_exp_f32_e32 v84, v84
	v_exp_f32_e32 v85, v85
	v_pk_mul_f32 v[40:41], v[162:163], v[40:41]
	v_cvt_pk_bf16_f32 v87, v34, v35
	v_cvt_pk_bf16_f32 v98, v40, v41
	v_rcp_f32_e32 v40, v84
	v_rcp_f32_e32 v41, v85
	v_pk_mul_f32 v[42:43], v[84:85], v[42:43]
	v_lshlrev_b32_e32 v165, 16, v157
	v_pk_mul_f32 v[36:37], v[164:165], v[36:37] op_sel_hi:[0,1]
	v_pk_mul_f32 v[40:41], v[82:83], v[40:41]
	v_cvt_pk_bf16_f32 v82, v42, v43
	v_pk_mul_f32 v[42:43], v[162:163], v[42:43]
	ds_write2_b32 v121, v86, v82 offset0:136 offset1:204
	v_cvt_pk_bf16_f32 v42, v42, v43
	ds_write2_b32 v39, v98, v42 offset0:136 offset1:204
	v_mov_b32_e32 v42, v34
	v_add_f32_e32 v34, v96, v169
	v_cvt_pk_bf16_f32 v82, v40, v41
	v_sub_f32_e32 v34, v34, v38
	ds_write2_b32 v102, v87, v82 offset0:136 offset1:204
	v_exp_f32_e32 v82, v34
	v_add_f32_e32 v34, v97, v170
	v_sub_f32_e32 v34, v34, v33
	v_exp_f32_e32 v83, v34
	v_mov_b32_e32 v43, v40
	v_mov_b32_e32 v40, v35
	v_rcp_f32_e32 v34, v82
	v_rcp_f32_e32 v35, v83
	v_pk_mul_f32 v[44:45], v[82:83], v[44:45]
	v_pk_mul_f32 v[42:43], v[164:165], v[42:43] op_sel_hi:[0,1]
	v_cvt_pk_bf16_f32 v39, v44, v45
	v_pk_mul_f32 v[34:35], v[80:81], v[34:35]
	v_add_f32_e32 v80, v94, v169
	v_add_f32_e32 v81, v95, v170
	v_sub_f32_e32 v80, v80, v38
	v_sub_f32_e32 v81, v81, v33
	v_exp_f32_e32 v80, v80
	v_exp_f32_e32 v81, v81
	v_pk_mul_f32 v[44:45], v[162:163], v[44:45]
	v_cvt_pk_bf16_f32 v82, v34, v35
	v_cvt_pk_bf16_f32 v83, v44, v45
	v_rcp_f32_e32 v44, v80
	v_rcp_f32_e32 v45, v81
	v_pk_mul_f32 v[46:47], v[80:81], v[46:47]
	v_add_u32_e32 v80, 0x400, v121
	v_add_u32_e32 v81, 0x4800, v121
	v_pk_mul_f32 v[44:45], v[78:79], v[44:45]
	v_cvt_pk_bf16_f32 v78, v46, v47
	ds_write2_b32 v80, v39, v78 offset0:16 offset1:84
	v_cvt_pk_bf16_f32 v39, v44, v45
	v_pk_mul_f32 v[46:47], v[162:163], v[46:47]
	ds_write2_b32 v81, v82, v39 offset0:16 offset1:84
	v_cvt_pk_bf16_f32 v39, v46, v47
	v_mov_b32_e32 v46, v34
	v_add_f32_e32 v34, v92, v169
	v_sub_f32_e32 v34, v34, v38
	v_exp_f32_e32 v78, v34
	v_add_f32_e32 v34, v93, v170
	v_sub_f32_e32 v34, v34, v33
	v_exp_f32_e32 v79, v34
; __device__ __forceinline__ float exp2_(float x) { return __builtin_amdgcn_exp2f(x); }
; __device__ __forceinline__ float rcp_(float x) { return __builtin_amdgcn_rcpf(x); }
; __device__ __forceinline__ float lo2f(unsigned u) { return __uint_as_float(u << 16); }
; __device__ __forceinline__ float hi2f(unsigned u) { return __uint_as_float(u & 0xffff0000u); }
; #define MFMA16(a, b, c) __builtin_amdgcn_mfma_f32_16x16x32_bf16((a), (b), (c), 0, 0, 0)
; __device__ __forceinline__ void hgrn_block(const Params& p, int bh, char* smem) {
;     ...
;       for (int r = 0; r < 8; ++r) {
;         const int t = wid * 8 + r;
;         float e0 = exp2_(gc[r][0] + off[0] - gmid[0]), e1 = exp2_(gc[r][1] + off[1] - gmid[1]);
;         float r0 = rcp_(e0), r1 = rcp_(e1);
;         float qa0 = qv[r][0] * e0, qa1 = qv[r][1] * e1;
;         float kb0 = kv[r][0] * r0, kb1 = kv[r][1] * r1;
;         *(unsigned*)(QA + t * 136 + d0) = pack2(qa0, qa1);
;         *(unsigned*)(KB + t * 136 + d0) = pack2(kb0, kb1);
;         *(unsigned*)(QIN + t * 136 + d0) = pack2(qa0 * egm[0], qa1 * egm[1]);
;         ks[0][r] = kb0 * eem[0];
;         ks[1][r] = kb1 * eem[1];
;         vs[0][r] = lo2f(vv[r]);
;         vs[1][r] = hi2f(vv[r]);
;       }
; #pragma unroll
;       for (int e = 0; e < 2; ++e) {
;         *(uint4*)(KSTT + (d0 + e) * 72 + wid * 8) = pack8(ks[e]);
;         *(uint4*)(VT + (d0 + e) * 72 + wid * 8) = pack8(vs[e]);
;       }
;     }
;     __syncthreads();
;     {
;       const int ti = wid >> 1;
; #pragma unroll
;       for (int q = 0; q < 2; ++q) {
;         const int si = (wid & 1) * 2 + q;
;         f32x4 a = f32x4{0.f, 0.f, 0.f, 0.f};
;         if (si <= ti) {
; #pragma unroll
;           for (int kk = 0; kk < 4; ++kk) {
;             bf16x8 kf = *(const bf16x8*)(KB + (si * 16 + fr) * 136 + kk * 32 + fq * 8);
;             bf16x8 qf = *(const bf16x8*)(QA + (ti * 16 + fr) * 136 + kk * 32 + fq * 8);
;             a = MFMA16(kf, qf, a);
;           }
;         }
;         const int t = ti * 16 + fr, s0 = si * 16 + fq * 4;
;         uint2 o;
;         o.x = pack2(s0 <= t ? a[0] : 0.f, s0 + 1 <= t ? a[1] : 0.f);
;         o.y = pack2(s0 + 2 <= t ? a[2] : 0.f, s0 + 3 <= t ? a[3] : 0.f);
;         *(uint2*)(AT + t * 72 + s0) = o;
;       }
	v_add_u32_e32 v82, 0x8c00, v121
	ds_write2_b32 v82, v83, v39 offset0:16 offset1:84
	v_add_f32_e32 v39, v88, v169
	v_sub_f32_e32 v38, v39, v38
	v_add_f32_e32 v39, v89, v170
	v_mov_b32_e32 v47, v44
	v_mov_b32_e32 v44, v35
	v_rcp_f32_e32 v34, v78
	v_rcp_f32_e32 v35, v79
	v_sub_f32_e32 v33, v39, v33
	v_exp_f32_e32 v38, v38
	v_exp_f32_e32 v39, v33
	v_pk_mul_f32 v[48:49], v[78:79], v[48:49]
	v_pk_mul_f32 v[34:35], v[76:77], v[34:35]
	v_cvt_pk_bf16_f32 v76, v48, v49
	v_pk_mul_f32 v[48:49], v[162:163], v[48:49]
	v_pk_mul_f32 v[46:47], v[164:165], v[46:47] op_sel_hi:[0,1]
	v_cvt_pk_bf16_f32 v33, v48, v49
	v_rcp_f32_e32 v48, v38
	v_rcp_f32_e32 v49, v39
	v_pk_mul_f32 v[38:39], v[38:39], v[160:161]
	v_lshlrev_b32_e32 v100, 16, v159
	v_lshlrev_b32_e32 v99, 16, v158
	v_pk_mul_f32 v[48:49], v[74:75], v[48:49]
	v_cvt_pk_bf16_f32 v74, v38, v39
	v_pk_mul_f32 v[38:39], v[162:163], v[38:39]
	v_lshlrev_b32_e32 v84, 16, v156
	v_cvt_pk_bf16_f32 v38, v38, v39
	ds_write2_b32 v82, v33, v38 offset0:152 offset1:220
	v_mov_b32_e32 v38, v34
	v_mov_b32_e32 v39, v48
	v_pk_mul_f32 v[38:39], v[164:165], v[38:39] op_sel_hi:[0,1]
	v_lshlrev_b32_e32 v86, 16, v155
	v_lshlrev_b32_e32 v83, 16, v154
	v_cvt_pk_bf16_f32 v77, v34, v35
	v_lshlrev_b32_e32 v78, 16, v153
	ds_write2_b32 v80, v76, v74 offset0:152 offset1:220
	v_cvt_pk_bf16_f32 v74, v48, v49
	v_mov_b32_e32 v48, v35
	v_lshlrev_b32_e32 v33, 16, v152
	v_cvt_pk_bf16_f32 v34, v36, v37
	v_cvt_pk_bf16_f32 v35, v42, v43
	v_cvt_pk_bf16_f32 v36, v46, v47
	v_cvt_pk_bf16_f32 v37, v38, v39
	v_pk_mul_f32 v[40:41], v[168:169], v[40:41] op_sel_hi:[0,1]
	v_pk_mul_f32 v[44:45], v[168:169], v[44:45] op_sel_hi:[0,1]
	ds_write2_b32 v81, v77, v74 offset0:152 offset1:220
	v_pk_mul_f32 v[48:49], v[168:169], v[48:49] op_sel_hi:[0,1]
	ds_write_b128 v122, v[34:37] offset:52224
	v_cvt_pk_bf16_f32 v34, v165, v100
	v_cvt_pk_bf16_f32 v35, v99, v84
	v_cvt_pk_bf16_f32 v36, v86, v83
	v_cvt_pk_bf16_f32 v37, v78, v33
	v_and_b32_e32 v157, 0xffff0000, v157
	v_and_b32_e32 v101, 0xffff0000, v159
	v_and_b32_e32 v103, 0xffff0000, v158
	v_and_b32_e32 v85, 0xffff0000, v156
	v_and_b32_e32 v87, 0xffff0000, v155
	v_and_b32_e32 v92, 0xffff0000, v154
	v_and_b32_e32 v79, 0xffff0000, v153
	v_and_b32_e32 v74, 0xffff0000, v152
	ds_write_b128 v123, v[34:37]
	v_cvt_pk_bf16_f32 v34, v90, v91
	v_cvt_pk_bf16_f32 v35, v40, v41
	v_cvt_pk_bf16_f32 v36, v44, v45
	v_cvt_pk_bf16_f32 v37, v48, v49
	ds_write_b128 v122, v[34:37] offset:52368
	v_cvt_pk_bf16_f32 v34, v157, v101
	v_cvt_pk_bf16_f32 v35, v103, v85
	v_cvt_pk_bf16_f32 v36, v87, v92
	v_cvt_pk_bf16_f32 v37, v79, v74
	v_mov_b32_e32 v32, 0
	ds_write_b128 v123, v[34:37] offset:144
	v_mov_b32_e32 v34, 0
	v_mov_b32_e32 v35, 0
	v_mov_b32_e32 v36, 0
	v_mov_b32_e32 v37, 0
	s_waitcnt lgkmcnt(0)
	s_barrier
	s_and_saveexec_b64 s[52:53], s[24:25]
	s_cbranch_execz .LBB0_605
	ds_read_b128 v[212:215], v50 offset:17408
	ds_read_b128 v[216:219], v52
	ds_read_b128 v[220:223], v50 offset:17472
	ds_read_b128 v[224:227], v52 offset:64
	ds_read_b128 v[228:231], v50 offset:17536
	ds_read_b128 v[232:235], v52 offset:128
	ds_read_b128 v[236:239], v50 offset:17600
	ds_read_b128 v[240:243], v52 offset:192
	s_waitcnt lgkmcnt(6)
	v_mfma_f32_16x16x32_bf16 v[34:37], v[212:215], v[216:219], 0
	s_waitcnt lgkmcnt(4)
	v_mfma_f32_16x16x32_bf16 v[34:37], v[220:223], v[224:227], v[34:37]
	s_waitcnt lgkmcnt(2)
	v_mfma_f32_16x16x32_bf16 v[34:37], v[228:231], v[232:235], v[34:37]
	s_waitcnt lgkmcnt(0)
	v_mfma_f32_16x16x32_bf16 v[34:37], v[236:239], v[240:243], v[34:37]
.LBB0_605:
	s_or_b64 exec, exec, s[52:53]
	s_nop 6
	v_cndmask_b32_e64 v33, v34, 0, s[28:29]
	v_cndmask_b32_e64 v34, 0, v35, s[30:31]
	v_cvt_pk_bf16_f32 v34, v33, v34
	v_cndmask_b32_e64 v33, v36, 0, s[34:35]
	v_cndmask_b32_e64 v35, v37, 0, s[36:37]
	v_cvt_pk_bf16_f32 v35, v33, v35
	ds_write_b64 v124, v[34:35]
	v_mov_b32_e32 v33, 0
	v_mov_b32_e32 v34, 0
	v_mov_b32_e32 v35, 0
	s_and_saveexec_b64 s[52:53], s[26:27]
	s_cbranch_execz .LBB0_607
	ds_read_b128 v[212:215], v126 offset:17408
	ds_read_b128 v[216:219], v52
	ds_read_b128 v[220:223], v126 offset:17472
	ds_read_b128 v[224:227], v52 offset:64
	ds_read_b128 v[228:231], v126 offset:17536
	ds_read_b128 v[232:235], v52 offset:128
	ds_read_b128 v[236:239], v126 offset:17600
	ds_read_b128 v[240:243], v52 offset:192
	s_waitcnt lgkmcnt(6)
	v_mfma_f32_16x16x32_bf16 v[32:35], v[212:215], v[216:219], 0
	s_waitcnt lgkmcnt(4)
	v_mfma_f32_16x16x32_bf16 v[32:35], v[220:223], v[224:227], v[32:35]
	s_waitcnt lgkmcnt(2)
	v_mfma_f32_16x16x32_bf16 v[32:35], v[228:231], v[232:235], v[32:35]
	s_waitcnt lgkmcnt(0)
	v_mfma_f32_16x16x32_bf16 v[32:35], v[236:239], v[240:243], v[32:35]
; #define MFMA16(a, b, c) __builtin_amdgcn_mfma_f32_16x16x32_bf16((a), (b), (c), 0, 0, 0)
; __device__ __forceinline__ void hgrn_block(const Params& p, int bh, char* smem) {
;     ...
;         const int t = ti * 16 + fr, s0 = si * 16 + fq * 4;
;         uint2 o;
;         o.x = pack2(s0 <= t ? a[0] : 0.f, s0 + 1 <= t ? a[1] : 0.f);
;         o.y = pack2(s0 + 2 <= t ? a[2] : 0.f, s0 + 3 <= t ? a[3] : 0.f);
;         *(uint2*)(AT + t * 72 + s0) = o;
;       }
;     }
;     __syncthreads();
;     f32x4 oc[4];
;     {
; #pragma unroll
;       for (int i = 0; i < 4; ++i) oc[i] = f32x4{0.f, 0.f, 0.f, 0.f};
; #pragma unroll
;       for (int kk = 0; kk < 2; ++kk) {
;         bf16x8 af = *(const bf16x8*)(AT + (tt * 16 + fr) * 72 + kk * 32 + fq * 8);
; #pragma unroll
;         for (int i = 0; i < 4; ++i) {
;           bf16x8 vf = *(const bf16x8*)(VT + ((vh * 4 + i) * 16 + fr) * 72 + kk * 32 + fq * 8);
;           oc[i] = MFMA16(vf, af, oc[i]);
;         }
;       }
; #pragma unroll
;       for (int kk = 0; kk < 4; ++kk) {
;         bf16x8 qf = *(const bf16x8*)(QIN + (tt * 16 + fr) * 136 + kk * 32 + fq * 8);
; #pragma unroll
;         for (int i = 0; i < 4; ++i) {
;           bf16x8 sf = *(const bf16x8*)(STT + ((vh * 4 + i) * 16 + fr) * 136 + kk * 32 + fq * 8);
;           oc[i] = MFMA16(sf, qf, oc[i]);
;         }
;       }
;       float s2 = 0.f;
; #pragma unroll
;       for (int i = 0; i < 4; ++i) s2 += oc[i][0] * oc[i][0] + oc[i][1] * oc[i][1] + oc[i][2] * oc[i][2] + oc[i][3] * oc[i][3];
;       s2 += __shfl_xor(s2, 16);
;       s2 += __shfl_xor(s2, 32);
;       if (fq == 0) ssq[vh * 64 + tt * 16 + fr] = s2;
.LBB0_607:
	s_or_b64 exec, exec, s[52:53]
	s_nop 6
	v_cndmask_b32_e64 v32, v32, 0, s[38:39]
	v_cndmask_b32_e64 v33, 0, v33, s[40:41]
	v_cvt_pk_bf16_f32 v32, v32, v33
	v_cndmask_b32_e64 v33, v34, 0, s[42:43]
	v_cndmask_b32_e64 v34, v35, 0, s[44:45]
	v_cvt_pk_bf16_f32 v33, v33, v34
	ds_write_b64 v124, v[32:33] offset:32
	s_waitcnt lgkmcnt(0)
	s_barrier
	ds_read_b128 v[212:215], v53
	ds_read_b128 v[220:223], v127
	ds_read_b128 v[224:227], v127 offset:2304
	ds_read_b128 v[228:231], v127 offset:4608
	ds_read_b128 v[232:235], v127 offset:6912
	ds_read_b128 v[216:219], v53 offset:64
	ds_read_b128 v[236:239], v127 offset:64
	ds_read_b128 v[240:243], v127 offset:2368
	ds_read_b128 v[174:177], v127 offset:4672
	ds_read_b128 v[178:181], v127 offset:6976
	ds_read_b128 v[74:77], v116 offset:34816
	ds_read_b128 v[78:81], v128
	ds_read_b128 v[182:185], v128 offset:4352
	ds_read_b128 v[186:189], v128 offset:8704
	ds_read_b128 v[190:193], v128 offset:13056
	s_waitcnt lgkmcnt(13)
	v_mfma_f32_16x16x32_bf16 v[44:47], v[220:223], v[212:215], 0
	s_waitcnt lgkmcnt(12)
	v_mfma_f32_16x16x32_bf16 v[40:43], v[224:227], v[212:215], 0
	s_waitcnt lgkmcnt(11)
	v_mfma_f32_16x16x32_bf16 v[36:39], v[228:231], v[212:215], 0
	s_waitcnt lgkmcnt(10)
	v_mfma_f32_16x16x32_bf16 v[32:35], v[232:235], v[212:215], 0
	s_waitcnt lgkmcnt(8)
	v_mfma_f32_16x16x32_bf16 v[44:47], v[236:239], v[216:219], v[44:47]
	s_waitcnt lgkmcnt(7)
	v_mfma_f32_16x16x32_bf16 v[40:43], v[240:243], v[216:219], v[40:43]
	s_waitcnt lgkmcnt(6)
	v_mfma_f32_16x16x32_bf16 v[36:39], v[174:177], v[216:219], v[36:39]
	s_waitcnt lgkmcnt(5)
	v_mfma_f32_16x16x32_bf16 v[32:35], v[178:181], v[216:219], v[32:35]
	ds_read_b128 v[212:215], v116 offset:34880
	ds_read_b128 v[216:219], v128 offset:64
	ds_read_b128 v[220:223], v128 offset:4416
	ds_read_b128 v[224:227], v128 offset:8768
	ds_read_b128 v[228:231], v128 offset:13120
	s_waitcnt lgkmcnt(8)
	v_mfma_f32_16x16x32_bf16 v[44:47], v[78:81], v[74:77], v[44:47]
	s_waitcnt lgkmcnt(7)
	v_mfma_f32_16x16x32_bf16 v[40:43], v[182:185], v[74:77], v[40:43]
	s_waitcnt lgkmcnt(6)
	v_mfma_f32_16x16x32_bf16 v[36:39], v[186:189], v[74:77], v[36:39]
	s_waitcnt lgkmcnt(5)
	v_mfma_f32_16x16x32_bf16 v[32:35], v[190:193], v[74:77], v[32:35]
	ds_read_b128 v[74:77], v116 offset:34944
	ds_read_b128 v[78:81], v128 offset:128
	ds_read_b128 v[182:185], v128 offset:4480
	ds_read_b128 v[186:189], v128 offset:8832
	ds_read_b128 v[190:193], v128 offset:13184
	s_waitcnt lgkmcnt(8)
	v_mfma_f32_16x16x32_bf16 v[44:47], v[216:219], v[212:215], v[44:47]
	s_waitcnt lgkmcnt(7)
	v_mfma_f32_16x16x32_bf16 v[40:43], v[220:223], v[212:215], v[40:43]
	s_waitcnt lgkmcnt(6)
	v_mfma_f32_16x16x32_bf16 v[36:39], v[224:227], v[212:215], v[36:39]
	s_waitcnt lgkmcnt(5)
	v_mfma_f32_16x16x32_bf16 v[32:35], v[228:231], v[212:215], v[32:35]
	ds_read_b128 v[212:215], v116 offset:35008
	ds_read_b128 v[216:219], v128 offset:192
	ds_read_b128 v[220:223], v128 offset:4544
	ds_read_b128 v[224:227], v128 offset:8896
	ds_read_b128 v[228:231], v128 offset:13248
	s_waitcnt lgkmcnt(8)
	v_mfma_f32_16x16x32_bf16 v[44:47], v[78:81], v[74:77], v[44:47]
	s_waitcnt lgkmcnt(7)
	v_mfma_f32_16x16x32_bf16 v[40:43], v[182:185], v[74:77], v[40:43]
	s_waitcnt lgkmcnt(6)
	v_mfma_f32_16x16x32_bf16 v[36:39], v[186:189], v[74:77], v[36:39]
	s_waitcnt lgkmcnt(5)
	v_mfma_f32_16x16x32_bf16 v[32:35], v[190:193], v[74:77], v[32:35]
	s_waitcnt lgkmcnt(3)
	v_mfma_f32_16x16x32_bf16 v[44:47], v[216:219], v[212:215], v[44:47]
	s_waitcnt lgkmcnt(2)
	v_mfma_f32_16x16x32_bf16 v[40:43], v[220:223], v[212:215], v[40:43]
	s_waitcnt lgkmcnt(1)
	v_mfma_f32_16x16x32_bf16 v[36:39], v[224:227], v[212:215], v[36:39]
	s_waitcnt lgkmcnt(0)
	v_mfma_f32_16x16x32_bf16 v[32:35], v[228:231], v[212:215], v[32:35]
	s_nop 7
	v_mul_f32_e32 v48, v45, v45
	v_fmac_f32_e32 v48, v44, v44
	v_mul_f32_e32 v49, v41, v41
	v_fmac_f32_e32 v49, v40, v40
	v_fmac_f32_e32 v48, v46, v46
	v_fmac_f32_e32 v49, v42, v42
	v_fmac_f32_e32 v48, v47, v47
	v_fmac_f32_e32 v49, v43, v43
	v_add_f32_e32 v48, v48, v49
	v_mul_f32_e32 v49, v37, v37
	v_fmac_f32_e32 v49, v36, v36
	v_fmac_f32_e32 v49, v38, v38
	v_fmac_f32_e32 v49, v39, v39
	v_add_f32_e32 v48, v48, v49
	v_mul_f32_e32 v49, v33, v33
	v_fmac_f32_e32 v49, v32, v32
	v_fmac_f32_e32 v49, v34, v34
	v_fmac_f32_e32 v49, v35, v35
	v_add_f32_e32 v48, v48, v49
	ds_bpermute_b32 v49, v117, v48
	s_waitcnt lgkmcnt(0)
	v_add_f32_e32 v48, v48, v49
	ds_bpermute_b32 v49, v118, v48
	s_and_saveexec_b64 s[52:53], s[6:7]
	s_cbranch_execz .LBB0_598
	s_waitcnt lgkmcnt(0)
	v_add_f32_e32 v48, v48, v49
	ds_write_b32 v129, v48
	s_branch .LBB0_598
